# carry tile index in SGPR across NSA loop iterations (drop tl[k] LDS re-read; window tiles consecutive), on top of threshold rescale
# baseline (speedup 1.0000x reference)
.LBB0_1204:
	s_or_b64 exec, exec, s[12:13]
	s_waitcnt vmcnt(0)
	v_mov_b32_e32 v26, v23
	v_mov_b32_e32 v27, v24
	v_lshlrev_b32_e32 v34, 16, v10
	v_and_b32_e32 v35, 0xffff0000, v6
	v_mov_b32_e32 v39, v24
	v_mov_b32_e32 v24, v23
	v_mov_b32_e32 v23, v25
	v_lshlrev_b32_e32 v36, 16, v6
	v_and_b32_e32 v37, 0xffff0000, v10
	v_mov_b32_e32 v38, v22
	v_pk_mul_f32 v[22:23], v[22:23], v[34:35]
	v_lshlrev_b32_e32 v6, 16, v7
	v_pk_fma_f32 v[22:23], v[26:27], v[36:37], v[22:23]
	v_mov_b32_e32 v29, v20
	v_cvt_pk_bf16_f32 v126, v22, v23
	v_lshlrev_b32_e32 v22, 16, v11
	v_and_b32_e32 v23, 0xffff0000, v7
	v_and_b32_e32 v7, 0xffff0000, v11
	v_mov_b32_e32 v42, v34
	v_mov_b32_e32 v43, v37
	v_mov_b32_e32 v11, v20
	v_mov_b32_e32 v20, v19
	v_mov_b32_e32 v26, v22
	v_mov_b32_e32 v27, v7
	v_pk_mul_f32 v[42:43], v[24:25], v[42:43]
	v_mov_b32_e32 v10, v18
	v_mov_b32_e32 v24, v6
	v_mov_b32_e32 v25, v23
	v_pk_mul_f32 v[26:27], v[20:21], v[26:27]
	v_mov_b32_e32 v28, v19
	v_pk_fma_f32 v[10:11], v[10:11], v[24:25], v[26:27] neg_lo:[0,0,1] neg_hi:[0,0,1]
	v_mov_b32_e32 v19, v21
	v_cvt_pk_bf16_f32 v123, v10, v11
	v_pk_mul_f32 v[10:11], v[18:19], v[22:23]
	v_mov_b32_e32 v30, v15
	v_pk_fma_f32 v[6:7], v[28:29], v[6:7], v[10:11]
	v_mov_b32_e32 v31, v16
	v_cvt_pk_bf16_f32 v127, v6, v7
	v_lshlrev_b32_e32 v6, 16, v12
	v_and_b32_e32 v7, 0xffff0000, v8
	v_mov_b32_e32 v19, v16
	v_mov_b32_e32 v16, v15
	v_mov_b32_e32 v15, v17
	v_lshlrev_b32_e32 v10, 16, v8
	v_and_b32_e32 v11, 0xffff0000, v12
	v_mov_b32_e32 v21, v7
	v_mov_b32_e32 v22, v6
	v_pk_mul_f32 v[6:7], v[14:15], v[6:7]
	v_lshlrev_b32_e32 v8, 16, v9
	v_pk_fma_f32 v[6:7], v[30:31], v[10:11], v[6:7]
	v_mov_b32_e32 v32, v3
	v_cvt_pk_bf16_f32 v128, v6, v7
	v_lshlrev_b32_e32 v6, 16, v13
	v_and_b32_e32 v7, 0xffff0000, v9
	v_and_b32_e32 v9, 0xffff0000, v13
	v_mov_b32_e32 v33, v4
	v_mov_b32_e32 v18, v14
	v_mov_b32_e32 v23, v11
	v_mov_b32_e32 v11, v4
	v_mov_b32_e32 v4, v3
	v_mov_b32_e32 v14, v6
	v_mov_b32_e32 v15, v9
	v_mov_b32_e32 v3, v5
	v_mov_b32_e32 v40, v36
	v_mov_b32_e32 v41, v35
	v_mov_b32_e32 v20, v10
	v_pk_mul_f32 v[22:23], v[16:17], v[22:23]
	v_mov_b32_e32 v10, v2
	v_mov_b32_e32 v12, v8
	v_mov_b32_e32 v13, v7
	v_pk_mul_f32 v[14:15], v[4:5], v[14:15]
	v_pk_mul_f32 v[2:3], v[2:3], v[6:7]
	v_pk_fma_f32 v[38:39], v[38:39], v[40:41], v[42:43] neg_lo:[0,0,1] neg_hi:[0,0,1]
	v_pk_fma_f32 v[18:19], v[18:19], v[20:21], v[22:23] neg_lo:[0,0,1] neg_hi:[0,0,1]
	v_pk_fma_f32 v[10:11], v[10:11], v[12:13], v[14:15] neg_lo:[0,0,1] neg_hi:[0,0,1]
	v_pk_fma_f32 v[2:3], v[32:33], v[8:9], v[2:3]
	s_lshl_b64 s[20:21], s[82:83], 19
	v_cvt_pk_bf16_f32 v122, v38, v39
	v_cvt_pk_bf16_f32 v124, v18, v19
	v_cvt_pk_bf16_f32 v125, v10, v11
	v_cvt_pk_bf16_f32 v129, v2, v3
	s_cmp_eq_u64 s[0:1], 0
	s_mov_b32 s16, 0
	s_waitcnt lgkmcnt(0)
	s_barrier
	s_cbranch_scc1 .LBB0_1228
	v_mov_b32_e32 v0, s92
	ds_read_b32 v2, v0
	s_bcnt1_i32_b64 s24, s[0:1]
	s_lshl_b64 s[0:1], s[20:21], 1
	s_add_u32 s14, s97, s0
	s_addc_u32 s15, s96, s1
	s_add_u32 s0, s52, s0
	s_waitcnt lgkmcnt(0)
	v_ashrrev_i32_e32 v3, 31, v2
	v_readfirstlane_b32 s99, v2
	s_addc_u32 s1, s53, s1
	v_lshlrev_b64 v[4:5], 14, v[2:3]
	v_lshl_add_u64 v[4:5], s[0:1], 0, v[4:5]
	v_lshl_add_u64 v[4:5], v[4:5], 0, v[146:147]
	v_lshlrev_b64 v[2:3], 7, v[2:3]
	v_add_co_u32_e32 v6, vcc, s35, v4
	v_lshl_add_u64 v[2:3], s[14:15], 0, v[2:3]
	s_nop 0
	v_addc_co_u32_e32 v7, vcc, 0, v5, vcc
	v_lshl_add_u64 v[2:3], v[2:3], 0, v[162:163]
	s_mov_b32 s12, 0x80000
	global_load_dwordx4 v[64:67], v[4:5], off
	global_load_dwordx4 v[68:71], v[6:7], off
	v_add_co_u32_e32 v4, vcc, s12, v2
	v_mov_b32_e32 v14, v1
	s_nop 0
	v_addc_co_u32_e32 v5, vcc, 0, v3, vcc
	global_load_dwordx4 v[72:75], v[2:3], off
	global_load_dwordx4 v[76:79], v[4:5], off
	v_mov_b32_e32 v15, v1
	v_mov_b32_e32 v0, v1
	v_mov_b32_e32 v2, v1
	v_mov_b32_e32 v3, v1
	v_mov_b32_e32 v4, v1
	v_mov_b32_e32 v5, v1
	v_mov_b32_e32 v6, v1
	v_mov_b32_e32 v7, v1
	v_mov_b32_e32 v8, v1
	v_mov_b32_e32 v9, v1
	v_mov_b32_e32 v10, v1
	v_mov_b32_e32 v11, v1
	v_mov_b32_e32 v12, v1
	v_mov_b32_e32 v13, v1
	v_mov_b64_e32 v[30:31], v[14:15]
	v_mov_b64_e32 v[46:47], v[14:15]
	v_mov_b64_e32 v[62:63], v[14:15]
	v_cmp_lt_i32_e64 s[12:13], -1, v168
	v_mov_b32_e32 v80, 0
	v_mov_b32_e32 v235, 0xf149f2ca
	v_mov_b32_e32 v130, 0
	v_mov_b32_e32 v131, 0
	v_mov_b32_e32 v132, 0
	v_mov_b32_e32 v133, 0
	v_mov_b32_e32 v134, 0
	v_mov_b32_e32 v135, 0
	v_mov_b32_e32 v136, 0
	v_mov_b32_e32 v137, 0
	v_mov_b64_e32 v[28:29], v[12:13]
	v_mov_b64_e32 v[26:27], v[10:11]
	v_mov_b64_e32 v[24:25], v[8:9]
	v_mov_b64_e32 v[22:23], v[6:7]
	v_mov_b64_e32 v[20:21], v[4:5]
	v_mov_b64_e32 v[18:19], v[2:3]
	v_mov_b64_e32 v[16:17], v[0:1]
	v_mov_b64_e32 v[44:45], v[12:13]
	v_mov_b64_e32 v[42:43], v[10:11]
	v_mov_b64_e32 v[40:41], v[8:9]
	v_mov_b64_e32 v[38:39], v[6:7]
	v_mov_b64_e32 v[36:37], v[4:5]
	v_mov_b64_e32 v[34:35], v[2:3]
	v_mov_b64_e32 v[32:33], v[0:1]
	v_mov_b64_e32 v[60:61], v[12:13]
	v_mov_b64_e32 v[58:59], v[10:11]
	v_mov_b64_e32 v[56:57], v[8:9]
	v_mov_b64_e32 v[54:55], v[6:7]
	v_mov_b64_e32 v[52:53], v[4:5]
	v_mov_b64_e32 v[50:51], v[2:3]
	v_mov_b64_e32 v[48:49], v[0:1]
	v_lshl_add_u64 v[172:173], s[14:15], 0, v[162:163]
	s_add_i32 s25, 0, 0x1bb04
	v_lshl_add_u64 v[174:175], s[0:1], 0, v[146:147]
	s_waitcnt vmcnt(3)
	ds_write_b128 v225, v[64:67]
	s_waitcnt vmcnt(2)
	ds_write_b128 v225, v[68:71] offset:8704
	s_waitcnt vmcnt(1)
	ds_write2_b64 v167, v[72:73], v[74:75] offset0:128 offset1:130
	s_waitcnt vmcnt(0)
	ds_write2_b64 v232, v[76:77], v[78:79] offset1:2
	v_mov_b64_e32 v[78:79], v[14:15]
	v_mov_b64_e32 v[76:77], v[12:13]
	v_mov_b64_e32 v[74:75], v[10:11]
	v_mov_b64_e32 v[72:73], v[8:9]
	v_mov_b64_e32 v[70:71], v[6:7]
	v_mov_b64_e32 v[68:69], v[4:5]
	v_mov_b64_e32 v[66:67], v[2:3]
	v_mov_b64_e32 v[64:65], v[0:1]
	s_waitcnt lgkmcnt(0)
	s_barrier
.LBB0_1206:
	v_mov_b32_e32 v0, s99
	s_add_i32 s26, s16, 1
	s_cmp_lt_u32 s26, s24
	s_cselect_b64 s[0:1], -1, 0
	s_cmp_ge_u32 s26, s24
	v_mov_b32_e32 v14, v0
	s_cbranch_scc1 .LBB0_1208
	v_mov_b32_e32 v10, s25
	ds_read_b32 v14, v10
.LBB0_1208:
	v_cndmask_b32_e64 v10, 0, 1, s[0:1]
	v_cmp_ne_u32_e64 s[14:15], 1, v10
	s_andn2_b64 vcc, exec, s[0:1]
	s_waitcnt lgkmcnt(0)
	v_ashrrev_i32_e32 v15, 31, v14
	v_readfirstlane_b32 s99, v14
	s_cbranch_vccnz .LBB0_1210
	s_waitcnt vmcnt(1)
	v_lshlrev_b64 v[2:3], 14, v[14:15]
	v_lshl_add_u64 v[2:3], v[174:175], 0, v[2:3]
	s_waitcnt vmcnt(0)
	v_add_co_u32_e32 v6, vcc, 0x2000, v2
	s_nop 1
	v_addc_co_u32_e32 v7, vcc, 0, v3, vcc
	global_load_dwordx4 v[2:5], v[2:3], off
	s_nop 0
	global_load_dwordx4 v[6:9], v[6:7], off

.LBB0_1229:
	ds_bpermute_b32 v0, v191, v80
	s_waitcnt vmcnt(0)
	v_mov_b32_e32 v8, v177
	s_waitcnt lgkmcnt(0)
	v_add_f32_e32 v0, v80, v0
	v_and_b32_e32 v4, 31, v8
	v_rcp_f32_e32 v2, v0
	s_nop 0
	v_mul_f32_e32 v2, 1.0, v2
	v_cmp_lt_f32_e32 vcc, 0, v0
	v_mul_u32_u24_e32 v6, 0x110, v4
	s_nop 0
	v_cndmask_b32_e32 v0, 0, v2, vcc
	v_pk_mul_f32 v[2:3], v[64:65], v[0:1] op_sel_hi:[1,0]
	v_pk_mul_f32 v[4:5], v[66:67], v[0:1] op_sel_hi:[1,0]
	v_cvt_pk_bf16_f32 v2, v2, v3
	v_cvt_pk_bf16_f32 v3, v4, v5
	v_ashrrev_i32_e32 v4, 2, v8
	v_and_b32_e32 v4, -8, v4
	v_add3_u32 v9, s95, v6, v4
	v_pk_mul_f32 v[4:5], v[68:69], v[0:1] op_sel_hi:[1,0]
	v_pk_mul_f32 v[6:7], v[70:71], v[0:1] op_sel_hi:[1,0]
	v_cvt_pk_bf16_f32 v4, v4, v5
	v_cvt_pk_bf16_f32 v5, v6, v7
	ds_write2_b64 v9, v[2:3], v[4:5] offset1:2
	v_pk_mul_f32 v[2:3], v[72:73], v[0:1] op_sel_hi:[1,0]
	v_pk_mul_f32 v[4:5], v[74:75], v[0:1] op_sel_hi:[1,0]
	v_cvt_pk_bf16_f32 v2, v2, v3
	v_cvt_pk_bf16_f32 v3, v4, v5
	v_pk_mul_f32 v[4:5], v[76:77], v[0:1] op_sel_hi:[1,0]
	v_pk_mul_f32 v[6:7], v[78:79], v[0:1] op_sel_hi:[1,0]
	v_cvt_pk_bf16_f32 v4, v4, v5
	v_cvt_pk_bf16_f32 v5, v6, v7
	ds_write2_b64 v9, v[2:3], v[4:5] offset0:4 offset1:6
	v_pk_mul_f32 v[2:3], v[48:49], v[0:1] op_sel_hi:[1,0]
	v_pk_mul_f32 v[4:5], v[50:51], v[0:1] op_sel_hi:[1,0]
	v_cvt_pk_bf16_f32 v2, v2, v3
	v_cvt_pk_bf16_f32 v3, v4, v5
	v_pk_mul_f32 v[4:5], v[52:53], v[0:1] op_sel_hi:[1,0]
	v_pk_mul_f32 v[6:7], v[54:55], v[0:1] op_sel_hi:[1,0]
	v_cvt_pk_bf16_f32 v4, v4, v5
	v_cvt_pk_bf16_f32 v5, v6, v7
	ds_write2_b64 v9, v[2:3], v[4:5] offset0:8 offset1:10
	v_pk_mul_f32 v[2:3], v[56:57], v[0:1] op_sel_hi:[1,0]
	v_pk_mul_f32 v[4:5], v[58:59], v[0:1] op_sel_hi:[1,0]
	v_cvt_pk_bf16_f32 v2, v2, v3
	v_cvt_pk_bf16_f32 v3, v4, v5
	v_pk_mul_f32 v[4:5], v[60:61], v[0:1] op_sel_hi:[1,0]
	v_pk_mul_f32 v[6:7], v[62:63], v[0:1] op_sel_hi:[1,0]
	v_cvt_pk_bf16_f32 v4, v4, v5
	v_cvt_pk_bf16_f32 v5, v6, v7
	ds_write2_b64 v9, v[2:3], v[4:5] offset0:12 offset1:14
	v_pk_mul_f32 v[2:3], v[32:33], v[0:1] op_sel_hi:[1,0]
	v_pk_mul_f32 v[4:5], v[34:35], v[0:1] op_sel_hi:[1,0]
	v_cvt_pk_bf16_f32 v2, v2, v3
	v_cvt_pk_bf16_f32 v3, v4, v5
	v_pk_mul_f32 v[4:5], v[36:37], v[0:1] op_sel_hi:[1,0]
	v_pk_mul_f32 v[6:7], v[38:39], v[0:1] op_sel_hi:[1,0]
	v_cvt_pk_bf16_f32 v4, v4, v5
	v_cvt_pk_bf16_f32 v5, v6, v7
	ds_write2_b64 v9, v[2:3], v[4:5] offset0:16 offset1:18
	v_pk_mul_f32 v[2:3], v[40:41], v[0:1] op_sel_hi:[1,0]
	v_pk_mul_f32 v[4:5], v[42:43], v[0:1] op_sel_hi:[1,0]
	v_cvt_pk_bf16_f32 v2, v2, v3
	v_cvt_pk_bf16_f32 v3, v4, v5
	v_pk_mul_f32 v[4:5], v[44:45], v[0:1] op_sel_hi:[1,0]
	v_pk_mul_f32 v[6:7], v[46:47], v[0:1] op_sel_hi:[1,0]
	v_cvt_pk_bf16_f32 v4, v4, v5
	v_cvt_pk_bf16_f32 v5, v6, v7
	ds_write2_b64 v9, v[2:3], v[4:5] offset0:20 offset1:22
	v_pk_mul_f32 v[2:3], v[16:17], v[0:1] op_sel_hi:[1,0]
	v_pk_mul_f32 v[4:5], v[18:19], v[0:1] op_sel_hi:[1,0]
	v_cvt_pk_bf16_f32 v2, v2, v3
	v_cvt_pk_bf16_f32 v3, v4, v5
	v_pk_mul_f32 v[4:5], v[20:21], v[0:1] op_sel_hi:[1,0]
	v_pk_mul_f32 v[6:7], v[22:23], v[0:1] op_sel_hi:[1,0]
	v_cvt_pk_bf16_f32 v4, v4, v5
	v_cvt_pk_bf16_f32 v5, v6, v7
	ds_write2_b64 v9, v[2:3], v[4:5] offset0:24 offset1:26
	v_pk_mul_f32 v[2:3], v[24:25], v[0:1] op_sel_hi:[1,0]
	v_pk_mul_f32 v[4:5], v[26:27], v[0:1] op_sel_hi:[1,0]
	v_cvt_pk_bf16_f32 v2, v2, v3
	v_cvt_pk_bf16_f32 v3, v4, v5
	v_pk_mul_f32 v[4:5], v[28:29], v[0:1] op_sel_hi:[1,0]
	v_pk_mul_f32 v[6:7], v[30:31], v[0:1] op_sel_hi:[1,0]
	v_cvt_pk_bf16_f32 v4, v4, v5
	v_cvt_pk_bf16_f32 v5, v6, v7
	ds_write2_b64 v9, v[2:3], v[4:5] offset0:28 offset1:30
	v_ashrrev_i32_e32 v2, 7, v8
	v_ashrrev_i32_e32 v3, 31, v2
	v_ashrrev_i32_e32 v29, 4, v8
	v_lshl_add_u64 v[2:3], s[80:81], 0, v[2:3]
	v_mov_b64_e32 v[20:21], s[48:49]
	v_lshlrev_b32_e32 v0, 4, v8
	v_and_or_b32 v6, v29, 7, s34
	v_mad_u64_u32 v[4:5], s[0:1], v2, s76, v[20:21]
	v_and_b32_e32 v18, 0xf0, v0
	v_mad_i32_i24 v5, v3, s76, v5
	v_lshlrev_b32_e32 v0, 8, v6
	v_lshl_add_u64 v[4:5], v[4:5], 0, v[0:1]
	v_mov_b32_e32 v19, v1
	v_lshl_add_u64 v[4:5], v[4:5], 0, v[18:19]
	v_add_co_u32_e32 v4, vcc, s35, v4
	s_waitcnt lgkmcnt(0)
	v_mov_b64_e32 v[22:23], s[50:51]
	s_nop 0
	v_addc_co_u32_e32 v5, vcc, 0, v5, vcc
	global_load_dwordx4 v[10:13], v[4:5], off
	global_load_dwordx4 v[40:43], v[4:5], off offset:1024
	v_add_co_u32_e32 v68, vcc, 0x6000, v4
	s_nop 1
	v_addc_co_u32_e32 v69, vcc, 0, v5, vcc
	global_load_dwordx4 v[44:47], v[68:69], off
	global_load_dwordx4 v[48:51], v[68:69], off offset:1024
	v_add_co_u32_e32 v68, vcc, 0xc000, v4
	s_nop 1
	v_addc_co_u32_e32 v69, vcc, 0, v5, vcc
	global_load_dwordx4 v[52:55], v[68:69], off
	global_load_dwordx4 v[56:59], v[68:69], off offset:1024
	v_add_co_u32_e32 v68, vcc, 0x12000, v4
	s_nop 1
	v_addc_co_u32_e32 v69, vcc, 0, v5, vcc
	global_load_dwordx4 v[60:63], v[68:69], off
	global_load_dwordx4 v[64:67], v[68:69], off offset:1024
	v_mad_u64_u32 v[4:5], s[0:1], v2, s77, v[22:23]
	v_mad_i32_i24 v5, v3, s77, v5
	v_lshlrev_b64 v[2:3], 13, v[2:3]
	v_lshl_add_u64 v[2:3], s[44:45], 0, v[2:3]
	v_lshlrev_b32_e32 v24, 2, v6
	v_mov_b32_e32 v25, v1
	v_lshl_add_u64 v[2:3], v[2:3], 0, v[0:1]
	v_lshl_add_u64 v[4:5], v[4:5], 0, v[24:25]
	v_lshl_add_u64 v[26:27], v[2:3], 0, v[18:19]
	global_load_dword v28, v[4:5], off offset:128
	global_load_dwordx4 v[6:9], v[26:27], off
	v_mul_lo_u32 v4, v29, s94
	v_add3_u32 v30, s95, v18, v4
	ds_read_b128 v[14:17], v30
	s_waitcnt vmcnt(2)
	v_lshlrev_b32_e32 v31, 16, v10
	v_and_b32_e32 v10, 0xffff0000, v10
	v_mul_f32_e32 v2, 0xbfb8aa3b, v31
	v_mul_f32_e32 v3, 0xbfb8aa3b, v10
	v_exp_f32_e32 v2, v2
	v_exp_f32_e32 v3, v3
	s_nop 0
	v_pk_add_f32 v[32:33], v[2:3], 1.0 op_sel_hi:[1,0]
	s_nop 0
	ds_read_b128 v[2:5], v30 offset:1088
	s_waitcnt lgkmcnt(1)
	v_lshlrev_b32_e32 v34, 16, v14
	v_and_b32_e32 v35, 0xffff0000, v14
	v_rcp_f32_e32 v14, v33
	s_nop 0
	v_mul_f32_e32 v33, v10, v14
	v_and_b32_e32 v38, 0xffff0000, v11
	v_rcp_f32_e32 v10, v32
	s_nop 0
	v_mul_f32_e32 v32, v31, v10
	v_lshlrev_b32_e32 v31, 16, v11
	v_mul_f32_e32 v11, 0xbfb8aa3b, v31
	v_exp_f32_e32 v36, v11
	v_mul_f32_e32 v11, 0xbfb8aa3b, v38
	v_exp_f32_e32 v37, v11
	s_waitcnt vmcnt(1)
	v_pk_mul_f32 v[34:35], v[28:29], v[34:35] op_sel_hi:[0,1]
	s_waitcnt vmcnt(0)
	v_lshlrev_b32_e32 v10, 16, v6
	v_and_b32_e32 v11, 0xffff0000, v6
	v_pk_fma_f32 v[10:11], v[34:35], v[32:33], v[10:11]
	v_lshlrev_b32_e32 v14, 16, v15
	v_cvt_pk_bf16_f32 v6, v10, v11
	v_pk_add_f32 v[10:11], v[36:37], 1.0 op_sel_hi:[1,0]
	v_and_b32_e32 v15, 0xffff0000, v15
	v_pk_mul_f32 v[14:15], v[28:29], v[14:15] op_sel_hi:[0,1]
	v_rcp_f32_e32 v32, v11
	s_nop 0
	v_mul_f32_e32 v11, v38, v32
	v_rcp_f32_e32 v32, v10
	s_nop 0
	v_mul_f32_e32 v10, v31, v32
	v_lshlrev_b32_e32 v31, 16, v12
	v_and_b32_e32 v12, 0xffff0000, v12
	v_mul_f32_e32 v33, 0xbfb8aa3b, v31
	v_exp_f32_e32 v34, v33
	v_mul_f32_e32 v33, 0xbfb8aa3b, v12
	v_exp_f32_e32 v35, v33
	v_lshlrev_b32_e32 v32, 16, v7
	v_and_b32_e32 v33, 0xffff0000, v7
	v_pk_fma_f32 v[10:11], v[14:15], v[10:11], v[32:33]
	v_lshlrev_b32_e32 v14, 16, v16
	v_cvt_pk_bf16_f32 v7, v10, v11
	v_pk_add_f32 v[10:11], v[34:35], 1.0 op_sel_hi:[1,0]
	v_and_b32_e32 v15, 0xffff0000, v16
	v_pk_mul_f32 v[14:15], v[28:29], v[14:15] op_sel_hi:[0,1]
	v_rcp_f32_e32 v16, v11
	s_nop 0
	v_mul_f32_e32 v11, v12, v16
	v_lshlrev_b32_e32 v16, 16, v13
	v_rcp_f32_e32 v12, v10
	s_nop 0
	v_mul_f32_e32 v10, v31, v12
	v_and_b32_e32 v31, 0xffff0000, v13
	v_mul_f32_e32 v13, 0xbfb8aa3b, v16
	v_exp_f32_e32 v32, v13
	v_mul_f32_e32 v13, 0xbfb8aa3b, v31
	v_exp_f32_e32 v33, v13
	v_lshlrev_b32_e32 v12, 16, v8
	v_and_b32_e32 v13, 0xffff0000, v8
	v_pk_fma_f32 v[10:11], v[14:15], v[10:11], v[12:13]
	v_lshlrev_b32_e32 v12, 16, v17
	v_cvt_pk_bf16_f32 v8, v10, v11
	v_pk_add_f32 v[10:11], v[32:33], 1.0 op_sel_hi:[1,0]
	v_and_b32_e32 v13, 0xffff0000, v17
	v_pk_mul_f32 v[12:13], v[28:29], v[12:13] op_sel_hi:[0,1]
	s_waitcnt lgkmcnt(0)
	v_and_b32_e32 v33, 0xffff0000, v2
	v_rcp_f32_e32 v14, v11
	s_nop 0
	v_mul_f32_e32 v11, v31, v14
	v_rcp_f32_e32 v14, v10
	s_nop 0
	v_mul_f32_e32 v10, v16, v14
	v_lshlrev_b32_e32 v14, 16, v9
	v_and_b32_e32 v15, 0xffff0000, v9
	v_pk_fma_f32 v[10:11], v[12:13], v[10:11], v[14:15]
	v_mov_b32_e32 v13, v1
	v_cvt_pk_bf16_f32 v9, v10, v11
	global_store_dwordx4 v[26:27], v[6:9], off
	v_mov_b32_e32 v17, v1
	v_lshlrev_b32_e32 v32, 16, v2
	v_add_u32_e32 v8, 4, v29
	v_ashrrev_i32_e32 v6, 3, v8
	v_ashrrev_i32_e32 v7, 31, v6
	v_lshl_add_u64 v[10:11], s[80:81], 0, v[6:7]
	v_and_or_b32 v16, v8, 7, s34
	v_mad_u64_u32 v[6:7], s[0:1], v10, s76, v[20:21]
	v_mad_i32_i24 v7, v11, s76, v7
	v_lshlrev_b32_e32 v12, 8, v16
	v_lshl_add_u64 v[6:7], v[6:7], 0, v[12:13]
	v_lshl_add_u64 v[6:7], v[6:7], 0, v[18:19]
	v_add_co_u32_e32 v6, vcc, s35, v6
	v_mad_u64_u32 v[14:15], s[0:1], v10, s77, v[22:23]
	s_nop 0
	v_addc_co_u32_e32 v7, vcc, 0, v7, vcc
	global_load_dwordx4 v[6:9], v[6:7], off
	v_mad_i32_i24 v15, v11, s77, v15
	v_lshlrev_b32_e32 v16, 2, v16
	v_lshl_add_u64 v[14:15], v[14:15], 0, v[16:17]
	global_load_dword v14, v[14:15], off offset:128
	v_lshlrev_b64 v[10:11], 13, v[10:11]
	v_lshl_add_u64 v[10:11], s[44:45], 0, v[10:11]
	v_lshl_add_u64 v[10:11], v[10:11], 0, v[12:13]
	v_lshl_add_u64 v[16:17], v[10:11], 0, v[18:19]
	global_load_dwordx4 v[10:13], v[16:17], off
	s_waitcnt vmcnt(2)
	v_lshlrev_b32_e32 v15, 16, v6
	v_and_b32_e32 v6, 0xffff0000, v6
	v_mul_f32_e32 v26, 0xbfb8aa3b, v15
	v_mul_f32_e32 v27, 0xbfb8aa3b, v6
	v_exp_f32_e32 v26, v26
	v_exp_f32_e32 v27, v27
	s_waitcnt vmcnt(1)
	v_pk_mul_f32 v[32:33], v[14:15], v[32:33] op_sel_hi:[0,1]
	v_pk_add_f32 v[26:27], v[26:27], 1.0 op_sel_hi:[1,0]
	s_nop 0
	s_nop 0
	v_rcp_f32_e32 v2, v27
	s_nop 0
	v_mul_f32_e32 v27, v6, v2
	v_rcp_f32_e32 v2, v26
	s_nop 0
	v_mul_f32_e32 v26, v15, v2
	v_lshlrev_b32_e32 v15, 16, v7
	v_and_b32_e32 v28, 0xffff0000, v7
	v_mul_f32_e32 v2, 0xbfb8aa3b, v15
	v_exp_f32_e32 v34, v2
	v_mul_f32_e32 v2, 0xbfb8aa3b, v28
	v_exp_f32_e32 v35, v2
	s_waitcnt vmcnt(0)
	v_lshlrev_b32_e32 v6, 16, v10
	v_and_b32_e32 v7, 0xffff0000, v10
	v_pk_fma_f32 v[6:7], v[32:33], v[26:27], v[6:7]
	v_lshlrev_b32_e32 v26, 16, v3
	v_cvt_pk_bf16_f32 v2, v6, v7
	v_pk_add_f32 v[6:7], v[34:35], 1.0 op_sel_hi:[1,0]
	v_and_b32_e32 v27, 0xffff0000, v3
	v_pk_mul_f32 v[26:27], v[14:15], v[26:27] op_sel_hi:[0,1]
	v_rcp_f32_e32 v3, v7
	s_nop 0
	v_mul_f32_e32 v7, v28, v3
	v_rcp_f32_e32 v3, v6
	s_nop 0
	v_mul_f32_e32 v6, v15, v3
	v_lshlrev_b32_e32 v15, 16, v8
	v_and_b32_e32 v8, 0xffff0000, v8
	v_mul_f32_e32 v3, 0xbfb8aa3b, v15
	v_exp_f32_e32 v32, v3
	v_mul_f32_e32 v3, 0xbfb8aa3b, v8
	v_exp_f32_e32 v33, v3
	v_lshlrev_b32_e32 v10, 16, v11
	v_and_b32_e32 v11, 0xffff0000, v11
	v_pk_fma_f32 v[6:7], v[26:27], v[6:7], v[10:11]
	v_lshlrev_b32_e32 v10, 16, v4
	v_cvt_pk_bf16_f32 v3, v6, v7
	v_pk_add_f32 v[6:7], v[32:33], 1.0 op_sel_hi:[1,0]
	v_and_b32_e32 v11, 0xffff0000, v4
	v_pk_mul_f32 v[10:11], v[14:15], v[10:11] op_sel_hi:[0,1]
	v_rcp_f32_e32 v4, v7
	s_nop 0
	v_mul_f32_e32 v7, v8, v4
	v_and_b32_e32 v28, 0xffff0000, v9
	v_rcp_f32_e32 v4, v6
	s_nop 0
	v_mul_f32_e32 v6, v15, v4
	v_lshlrev_b32_e32 v15, 16, v9
	v_mul_f32_e32 v4, 0xbfb8aa3b, v15
	v_exp_f32_e32 v26, v4
	v_mul_f32_e32 v4, 0xbfb8aa3b, v28
	v_exp_f32_e32 v27, v4
	v_lshlrev_b32_e32 v8, 16, v12
	v_and_b32_e32 v9, 0xffff0000, v12
	v_pk_fma_f32 v[6:7], v[10:11], v[6:7], v[8:9]
	v_lshlrev_b32_e32 v8, 16, v5
	v_cvt_pk_bf16_f32 v4, v6, v7
	v_pk_add_f32 v[6:7], v[26:27], 1.0 op_sel_hi:[1,0]
	v_and_b32_e32 v9, 0xffff0000, v5
	v_pk_mul_f32 v[8:9], v[14:15], v[8:9] op_sel_hi:[0,1]
	v_rcp_f32_e32 v5, v7
	s_nop 0
	v_mul_f32_e32 v7, v28, v5
	v_rcp_f32_e32 v5, v6
	s_nop 0
	v_mul_f32_e32 v6, v15, v5
	v_lshlrev_b32_e32 v10, 16, v13
	v_and_b32_e32 v11, 0xffff0000, v13
	v_pk_fma_f32 v[6:7], v[8:9], v[6:7], v[10:11]
	s_nop 0
	v_cvt_pk_bf16_f32 v5, v6, v7
	global_store_dwordx4 v[16:17], v[2:5], off
	ds_read_b128 v[14:17], v30 offset:2176
	s_nop 0
	v_add_u32_e32 v2, 8, v29
	v_ashrrev_i32_e32 v2, 3, v2
	v_ashrrev_i32_e32 v3, 31, v2
	v_lshl_add_u64 v[2:3], s[80:81], 0, v[2:3]
	v_mad_u64_u32 v[4:5], s[0:1], v2, s76, v[20:21]
	v_mad_i32_i24 v5, v3, s76, v5
	v_lshl_add_u64 v[4:5], v[4:5], 0, v[0:1]
	v_lshl_add_u64 v[4:5], v[4:5], 0, v[18:19]
	v_add_co_u32_e32 v4, vcc, s35, v4
	s_nop 1
	v_addc_co_u32_e32 v5, vcc, 0, v5, vcc
	global_load_dwordx4 v[10:13], v[4:5], off
	v_mad_u64_u32 v[4:5], s[0:1], v2, s77, v[22:23]
	v_mad_i32_i24 v5, v3, s77, v5
	v_lshlrev_b64 v[2:3], 13, v[2:3]
	v_lshl_add_u64 v[2:3], s[44:45], 0, v[2:3]
	v_lshl_add_u64 v[2:3], v[2:3], 0, v[0:1]
	v_lshl_add_u64 v[4:5], v[4:5], 0, v[24:25]
	v_lshl_add_u64 v[26:27], v[2:3], 0, v[18:19]
	global_load_dword v28, v[4:5], off offset:128
	global_load_dwordx4 v[6:9], v[26:27], off
	s_waitcnt vmcnt(2)
	v_lshlrev_b32_e32 v31, 16, v10
	v_and_b32_e32 v10, 0xffff0000, v10
	v_mul_f32_e32 v2, 0xbfb8aa3b, v31
	v_mul_f32_e32 v3, 0xbfb8aa3b, v10
	v_exp_f32_e32 v2, v2
	v_exp_f32_e32 v3, v3
	s_nop 0
	v_pk_add_f32 v[32:33], v[2:3], 1.0 op_sel_hi:[1,0]
	s_nop 0
	ds_read_b128 v[2:5], v30 offset:3264
	s_waitcnt lgkmcnt(1)
	v_lshlrev_b32_e32 v34, 16, v14
	v_and_b32_e32 v35, 0xffff0000, v14
	v_rcp_f32_e32 v14, v33
	s_nop 0
	v_mul_f32_e32 v33, v10, v14
	v_and_b32_e32 v38, 0xffff0000, v11
	v_rcp_f32_e32 v10, v32
	s_nop 0
	v_mul_f32_e32 v32, v31, v10
	v_lshlrev_b32_e32 v31, 16, v11
	v_mul_f32_e32 v11, 0xbfb8aa3b, v31
	v_exp_f32_e32 v36, v11
	v_mul_f32_e32 v11, 0xbfb8aa3b, v38
	v_exp_f32_e32 v37, v11
	s_waitcnt vmcnt(1)
	v_pk_mul_f32 v[34:35], v[28:29], v[34:35] op_sel_hi:[0,1]
	s_waitcnt vmcnt(0)
	v_lshlrev_b32_e32 v10, 16, v6
	v_and_b32_e32 v11, 0xffff0000, v6
	v_pk_fma_f32 v[10:11], v[34:35], v[32:33], v[10:11]
	v_lshlrev_b32_e32 v14, 16, v15
	v_cvt_pk_bf16_f32 v6, v10, v11
	v_pk_add_f32 v[10:11], v[36:37], 1.0 op_sel_hi:[1,0]
	v_and_b32_e32 v15, 0xffff0000, v15
	v_pk_mul_f32 v[14:15], v[28:29], v[14:15] op_sel_hi:[0,1]
	v_rcp_f32_e32 v32, v11
	s_nop 0
	v_mul_f32_e32 v11, v38, v32
	v_rcp_f32_e32 v32, v10
	s_nop 0
	v_mul_f32_e32 v10, v31, v32
	v_lshlrev_b32_e32 v31, 16, v12
	v_and_b32_e32 v12, 0xffff0000, v12
	v_mul_f32_e32 v33, 0xbfb8aa3b, v31
	v_exp_f32_e32 v34, v33
	v_mul_f32_e32 v33, 0xbfb8aa3b, v12
	v_exp_f32_e32 v35, v33
	v_lshlrev_b32_e32 v32, 16, v7
	v_and_b32_e32 v33, 0xffff0000, v7
	v_pk_fma_f32 v[10:11], v[14:15], v[10:11], v[32:33]
	v_lshlrev_b32_e32 v14, 16, v16
	v_cvt_pk_bf16_f32 v7, v10, v11
	v_pk_add_f32 v[10:11], v[34:35], 1.0 op_sel_hi:[1,0]
	v_and_b32_e32 v15, 0xffff0000, v16
	v_pk_mul_f32 v[14:15], v[28:29], v[14:15] op_sel_hi:[0,1]
	v_rcp_f32_e32 v16, v11
	s_nop 0
	v_mul_f32_e32 v11, v12, v16
	v_lshlrev_b32_e32 v16, 16, v13
	v_rcp_f32_e32 v12, v10
	s_nop 0
	v_mul_f32_e32 v10, v31, v12
	v_and_b32_e32 v31, 0xffff0000, v13
	v_mul_f32_e32 v13, 0xbfb8aa3b, v16
	v_exp_f32_e32 v32, v13
	v_mul_f32_e32 v13, 0xbfb8aa3b, v31
	v_exp_f32_e32 v33, v13
	v_lshlrev_b32_e32 v12, 16, v8
	v_and_b32_e32 v13, 0xffff0000, v8
	v_pk_fma_f32 v[10:11], v[14:15], v[10:11], v[12:13]
	v_lshlrev_b32_e32 v12, 16, v17
	v_cvt_pk_bf16_f32 v8, v10, v11
	v_pk_add_f32 v[10:11], v[32:33], 1.0 op_sel_hi:[1,0]
	v_and_b32_e32 v13, 0xffff0000, v17
	v_pk_mul_f32 v[12:13], v[28:29], v[12:13] op_sel_hi:[0,1]
	s_waitcnt lgkmcnt(0)
	v_and_b32_e32 v33, 0xffff0000, v2
	v_rcp_f32_e32 v14, v11
	s_nop 0
	v_mul_f32_e32 v11, v31, v14
	v_rcp_f32_e32 v14, v10
	s_nop 0
	v_mul_f32_e32 v10, v16, v14
	v_lshlrev_b32_e32 v14, 16, v9
	v_and_b32_e32 v15, 0xffff0000, v9
	v_pk_fma_f32 v[10:11], v[12:13], v[10:11], v[14:15]
	v_mov_b32_e32 v13, v1
	v_cvt_pk_bf16_f32 v9, v10, v11
	global_store_dwordx4 v[26:27], v[6:9], off
	v_mov_b32_e32 v17, v1
	v_lshlrev_b32_e32 v32, 16, v2
	v_add_u32_e32 v8, 12, v29
	v_ashrrev_i32_e32 v6, 3, v8
	v_ashrrev_i32_e32 v7, 31, v6
	v_lshl_add_u64 v[10:11], s[80:81], 0, v[6:7]
	v_and_or_b32 v16, v8, 7, s34
	v_mad_u64_u32 v[6:7], s[0:1], v10, s76, v[20:21]
	v_mad_i32_i24 v7, v11, s76, v7
	v_lshlrev_b32_e32 v12, 8, v16
	v_lshl_add_u64 v[6:7], v[6:7], 0, v[12:13]
	v_lshl_add_u64 v[6:7], v[6:7], 0, v[18:19]
	v_add_co_u32_e32 v6, vcc, s35, v6
	v_mad_u64_u32 v[14:15], s[0:1], v10, s77, v[22:23]
	s_nop 0
	v_addc_co_u32_e32 v7, vcc, 0, v7, vcc
	global_load_dwordx4 v[6:9], v[6:7], off
	v_mad_i32_i24 v15, v11, s77, v15
	v_lshlrev_b32_e32 v16, 2, v16
	v_lshl_add_u64 v[14:15], v[14:15], 0, v[16:17]
	global_load_dword v14, v[14:15], off offset:128
	v_lshlrev_b64 v[10:11], 13, v[10:11]
	v_lshl_add_u64 v[10:11], s[44:45], 0, v[10:11]
	v_lshl_add_u64 v[10:11], v[10:11], 0, v[12:13]
	v_lshl_add_u64 v[16:17], v[10:11], 0, v[18:19]
	global_load_dwordx4 v[10:13], v[16:17], off
	s_waitcnt vmcnt(2)
	v_lshlrev_b32_e32 v15, 16, v6
	v_and_b32_e32 v6, 0xffff0000, v6
	v_mul_f32_e32 v26, 0xbfb8aa3b, v15
	v_mul_f32_e32 v27, 0xbfb8aa3b, v6
	v_exp_f32_e32 v26, v26
	v_exp_f32_e32 v27, v27
	s_waitcnt vmcnt(1)
	v_pk_mul_f32 v[32:33], v[14:15], v[32:33] op_sel_hi:[0,1]
	v_pk_add_f32 v[26:27], v[26:27], 1.0 op_sel_hi:[1,0]
	s_nop 0
	s_nop 0
	v_rcp_f32_e32 v2, v27
	s_nop 0
	v_mul_f32_e32 v27, v6, v2
	v_rcp_f32_e32 v2, v26
	s_nop 0
	v_mul_f32_e32 v26, v15, v2
	v_lshlrev_b32_e32 v15, 16, v7
	v_and_b32_e32 v28, 0xffff0000, v7
	v_mul_f32_e32 v2, 0xbfb8aa3b, v15
	v_exp_f32_e32 v34, v2
	v_mul_f32_e32 v2, 0xbfb8aa3b, v28
	v_exp_f32_e32 v35, v2
	s_waitcnt vmcnt(0)
	v_lshlrev_b32_e32 v6, 16, v10
	v_and_b32_e32 v7, 0xffff0000, v10
	v_pk_fma_f32 v[6:7], v[32:33], v[26:27], v[6:7]
	v_lshlrev_b32_e32 v26, 16, v3
	v_cvt_pk_bf16_f32 v2, v6, v7
	v_pk_add_f32 v[6:7], v[34:35], 1.0 op_sel_hi:[1,0]
	v_and_b32_e32 v27, 0xffff0000, v3
	v_pk_mul_f32 v[26:27], v[14:15], v[26:27] op_sel_hi:[0,1]
	v_rcp_f32_e32 v3, v7
	s_nop 0
	v_mul_f32_e32 v7, v28, v3
	v_rcp_f32_e32 v3, v6
	s_nop 0
	v_mul_f32_e32 v6, v15, v3
	v_lshlrev_b32_e32 v15, 16, v8
	v_and_b32_e32 v8, 0xffff0000, v8
	v_mul_f32_e32 v3, 0xbfb8aa3b, v15
	v_exp_f32_e32 v32, v3
	v_mul_f32_e32 v3, 0xbfb8aa3b, v8
	v_exp_f32_e32 v33, v3
	v_lshlrev_b32_e32 v10, 16, v11
	v_and_b32_e32 v11, 0xffff0000, v11
	v_pk_fma_f32 v[6:7], v[26:27], v[6:7], v[10:11]
	v_lshlrev_b32_e32 v10, 16, v4
	v_cvt_pk_bf16_f32 v3, v6, v7
	v_pk_add_f32 v[6:7], v[32:33], 1.0 op_sel_hi:[1,0]
	v_and_b32_e32 v11, 0xffff0000, v4
	v_pk_mul_f32 v[10:11], v[14:15], v[10:11] op_sel_hi:[0,1]
	v_rcp_f32_e32 v4, v7
	s_nop 0
	v_mul_f32_e32 v7, v8, v4
	v_and_b32_e32 v28, 0xffff0000, v9
	v_rcp_f32_e32 v4, v6
	s_nop 0
	v_mul_f32_e32 v6, v15, v4
	v_lshlrev_b32_e32 v15, 16, v9
	v_mul_f32_e32 v4, 0xbfb8aa3b, v15
	v_exp_f32_e32 v26, v4
	v_mul_f32_e32 v4, 0xbfb8aa3b, v28
	v_exp_f32_e32 v27, v4
	v_lshlrev_b32_e32 v8, 16, v12
	v_and_b32_e32 v9, 0xffff0000, v12
	v_pk_fma_f32 v[6:7], v[10:11], v[6:7], v[8:9]
	v_lshlrev_b32_e32 v8, 16, v5
	v_cvt_pk_bf16_f32 v4, v6, v7
	v_pk_add_f32 v[6:7], v[26:27], 1.0 op_sel_hi:[1,0]
	v_and_b32_e32 v9, 0xffff0000, v5
	v_pk_mul_f32 v[8:9], v[14:15], v[8:9] op_sel_hi:[0,1]
	v_rcp_f32_e32 v5, v7
	s_nop 0
	v_mul_f32_e32 v7, v28, v5
	v_rcp_f32_e32 v5, v6
	s_nop 0
	v_mul_f32_e32 v6, v15, v5
	v_lshlrev_b32_e32 v10, 16, v13
	v_and_b32_e32 v11, 0xffff0000, v13
	v_pk_fma_f32 v[6:7], v[8:9], v[6:7], v[10:11]
	s_nop 0
	v_cvt_pk_bf16_f32 v5, v6, v7
	global_store_dwordx4 v[16:17], v[2:5], off
	ds_read_b128 v[14:17], v30 offset:4352
	s_nop 0
	v_add_u32_e32 v2, 16, v29
	v_ashrrev_i32_e32 v2, 3, v2
	v_ashrrev_i32_e32 v3, 31, v2
	v_lshl_add_u64 v[2:3], s[80:81], 0, v[2:3]
	v_mad_u64_u32 v[4:5], s[0:1], v2, s76, v[20:21]
	v_mad_i32_i24 v5, v3, s76, v5
	v_lshl_add_u64 v[4:5], v[4:5], 0, v[0:1]
	v_lshl_add_u64 v[4:5], v[4:5], 0, v[18:19]
	v_add_co_u32_e32 v4, vcc, s35, v4
	s_nop 1
	v_addc_co_u32_e32 v5, vcc, 0, v5, vcc
	global_load_dwordx4 v[10:13], v[4:5], off
	v_mad_u64_u32 v[4:5], s[0:1], v2, s77, v[22:23]
	v_mad_i32_i24 v5, v3, s77, v5
	v_lshlrev_b64 v[2:3], 13, v[2:3]
	v_lshl_add_u64 v[2:3], s[44:45], 0, v[2:3]
	v_lshl_add_u64 v[2:3], v[2:3], 0, v[0:1]
	v_lshl_add_u64 v[4:5], v[4:5], 0, v[24:25]
	v_lshl_add_u64 v[26:27], v[2:3], 0, v[18:19]
	global_load_dword v28, v[4:5], off offset:128
	global_load_dwordx4 v[6:9], v[26:27], off
	s_waitcnt vmcnt(2)
	v_lshlrev_b32_e32 v31, 16, v10
	v_and_b32_e32 v10, 0xffff0000, v10
	v_mul_f32_e32 v2, 0xbfb8aa3b, v31
	v_mul_f32_e32 v3, 0xbfb8aa3b, v10
	v_exp_f32_e32 v2, v2
	v_exp_f32_e32 v3, v3
	s_nop 0
	v_pk_add_f32 v[32:33], v[2:3], 1.0 op_sel_hi:[1,0]
	s_nop 0
	ds_read_b128 v[2:5], v30 offset:5440
	s_waitcnt lgkmcnt(1)
	v_lshlrev_b32_e32 v34, 16, v14
	v_and_b32_e32 v35, 0xffff0000, v14
	v_rcp_f32_e32 v14, v33
	s_nop 0
	v_mul_f32_e32 v33, v10, v14
	v_and_b32_e32 v38, 0xffff0000, v11
	v_rcp_f32_e32 v10, v32
	s_nop 0
	v_mul_f32_e32 v32, v31, v10
	v_lshlrev_b32_e32 v31, 16, v11
	v_mul_f32_e32 v11, 0xbfb8aa3b, v31
	v_exp_f32_e32 v36, v11
	v_mul_f32_e32 v11, 0xbfb8aa3b, v38
	v_exp_f32_e32 v37, v11
	s_waitcnt vmcnt(1)
	v_pk_mul_f32 v[34:35], v[28:29], v[34:35] op_sel_hi:[0,1]
	s_waitcnt vmcnt(0)
	v_lshlrev_b32_e32 v10, 16, v6
	v_and_b32_e32 v11, 0xffff0000, v6
	v_pk_fma_f32 v[10:11], v[34:35], v[32:33], v[10:11]
	v_lshlrev_b32_e32 v14, 16, v15
	v_cvt_pk_bf16_f32 v6, v10, v11
	v_pk_add_f32 v[10:11], v[36:37], 1.0 op_sel_hi:[1,0]
	v_and_b32_e32 v15, 0xffff0000, v15
	v_pk_mul_f32 v[14:15], v[28:29], v[14:15] op_sel_hi:[0,1]
	v_rcp_f32_e32 v32, v11
	s_nop 0
	v_mul_f32_e32 v11, v38, v32
	v_rcp_f32_e32 v32, v10
	s_nop 0
	v_mul_f32_e32 v10, v31, v32
	v_lshlrev_b32_e32 v31, 16, v12
	v_and_b32_e32 v12, 0xffff0000, v12
	v_mul_f32_e32 v33, 0xbfb8aa3b, v31
	v_exp_f32_e32 v34, v33
	v_mul_f32_e32 v33, 0xbfb8aa3b, v12
	v_exp_f32_e32 v35, v33
	v_lshlrev_b32_e32 v32, 16, v7
	v_and_b32_e32 v33, 0xffff0000, v7
	v_pk_fma_f32 v[10:11], v[14:15], v[10:11], v[32:33]
	v_lshlrev_b32_e32 v14, 16, v16
	v_cvt_pk_bf16_f32 v7, v10, v11
	v_pk_add_f32 v[10:11], v[34:35], 1.0 op_sel_hi:[1,0]
	v_and_b32_e32 v15, 0xffff0000, v16
	v_pk_mul_f32 v[14:15], v[28:29], v[14:15] op_sel_hi:[0,1]
	v_rcp_f32_e32 v16, v11
	s_nop 0
	v_mul_f32_e32 v11, v12, v16
	v_lshlrev_b32_e32 v16, 16, v13
	v_rcp_f32_e32 v12, v10
	s_nop 0
	v_mul_f32_e32 v10, v31, v12
	v_and_b32_e32 v31, 0xffff0000, v13
	v_mul_f32_e32 v13, 0xbfb8aa3b, v16
	v_exp_f32_e32 v32, v13
	v_mul_f32_e32 v13, 0xbfb8aa3b, v31
	v_exp_f32_e32 v33, v13
	v_lshlrev_b32_e32 v12, 16, v8
	v_and_b32_e32 v13, 0xffff0000, v8
	v_pk_fma_f32 v[10:11], v[14:15], v[10:11], v[12:13]
	v_lshlrev_b32_e32 v12, 16, v17
	v_cvt_pk_bf16_f32 v8, v10, v11
	v_pk_add_f32 v[10:11], v[32:33], 1.0 op_sel_hi:[1,0]
	v_and_b32_e32 v13, 0xffff0000, v17
	v_pk_mul_f32 v[12:13], v[28:29], v[12:13] op_sel_hi:[0,1]
	s_waitcnt lgkmcnt(0)
	v_and_b32_e32 v33, 0xffff0000, v2
	v_rcp_f32_e32 v14, v11
	s_nop 0
	v_mul_f32_e32 v11, v31, v14
	v_rcp_f32_e32 v14, v10
	s_nop 0
	v_mul_f32_e32 v10, v16, v14
	v_lshlrev_b32_e32 v14, 16, v9
	v_and_b32_e32 v15, 0xffff0000, v9
	v_pk_fma_f32 v[10:11], v[12:13], v[10:11], v[14:15]
	v_mov_b32_e32 v13, v1
	v_cvt_pk_bf16_f32 v9, v10, v11
	global_store_dwordx4 v[26:27], v[6:9], off
	v_mov_b32_e32 v17, v1
	v_lshlrev_b32_e32 v32, 16, v2
	v_add_u32_e32 v8, 20, v29
	v_ashrrev_i32_e32 v6, 3, v8
	v_ashrrev_i32_e32 v7, 31, v6
	v_lshl_add_u64 v[10:11], s[80:81], 0, v[6:7]
	v_and_or_b32 v16, v8, 7, s34
	v_mad_u64_u32 v[6:7], s[0:1], v10, s76, v[20:21]
	v_mad_i32_i24 v7, v11, s76, v7
	v_lshlrev_b32_e32 v12, 8, v16
	v_lshl_add_u64 v[6:7], v[6:7], 0, v[12:13]
	v_lshl_add_u64 v[6:7], v[6:7], 0, v[18:19]
	v_add_co_u32_e32 v6, vcc, s35, v6
	v_mad_u64_u32 v[14:15], s[0:1], v10, s77, v[22:23]
	s_nop 0
	v_addc_co_u32_e32 v7, vcc, 0, v7, vcc
	global_load_dwordx4 v[6:9], v[6:7], off
	v_mad_i32_i24 v15, v11, s77, v15
	v_lshlrev_b32_e32 v16, 2, v16
	v_lshl_add_u64 v[14:15], v[14:15], 0, v[16:17]
	global_load_dword v14, v[14:15], off offset:128
	v_lshlrev_b64 v[10:11], 13, v[10:11]
	v_lshl_add_u64 v[10:11], s[44:45], 0, v[10:11]
	v_lshl_add_u64 v[10:11], v[10:11], 0, v[12:13]
	v_lshl_add_u64 v[16:17], v[10:11], 0, v[18:19]
	global_load_dwordx4 v[10:13], v[16:17], off
	s_waitcnt vmcnt(2)
	v_lshlrev_b32_e32 v15, 16, v6
	v_and_b32_e32 v6, 0xffff0000, v6
	v_mul_f32_e32 v26, 0xbfb8aa3b, v15
	v_mul_f32_e32 v27, 0xbfb8aa3b, v6
	v_exp_f32_e32 v26, v26
	v_exp_f32_e32 v27, v27
	s_waitcnt vmcnt(1)
	v_pk_mul_f32 v[32:33], v[14:15], v[32:33] op_sel_hi:[0,1]
	v_pk_add_f32 v[26:27], v[26:27], 1.0 op_sel_hi:[1,0]
	s_nop 0
	s_nop 0
	v_rcp_f32_e32 v2, v27
	s_nop 0
	v_mul_f32_e32 v27, v6, v2
	v_rcp_f32_e32 v2, v26
	s_nop 0
	v_mul_f32_e32 v26, v15, v2
	v_lshlrev_b32_e32 v15, 16, v7
	v_and_b32_e32 v28, 0xffff0000, v7
	v_mul_f32_e32 v2, 0xbfb8aa3b, v15
	v_exp_f32_e32 v34, v2
	v_mul_f32_e32 v2, 0xbfb8aa3b, v28
	v_exp_f32_e32 v35, v2
	s_waitcnt vmcnt(0)
	v_lshlrev_b32_e32 v6, 16, v10
	v_and_b32_e32 v7, 0xffff0000, v10
	v_pk_fma_f32 v[6:7], v[32:33], v[26:27], v[6:7]
	v_lshlrev_b32_e32 v26, 16, v3
	v_cvt_pk_bf16_f32 v2, v6, v7
	v_pk_add_f32 v[6:7], v[34:35], 1.0 op_sel_hi:[1,0]
	v_and_b32_e32 v27, 0xffff0000, v3
	v_pk_mul_f32 v[26:27], v[14:15], v[26:27] op_sel_hi:[0,1]
	v_rcp_f32_e32 v3, v7
	s_nop 0
	v_mul_f32_e32 v7, v28, v3
	v_rcp_f32_e32 v3, v6
	s_nop 0
	v_mul_f32_e32 v6, v15, v3
	v_lshlrev_b32_e32 v15, 16, v8
	v_and_b32_e32 v8, 0xffff0000, v8
	v_mul_f32_e32 v3, 0xbfb8aa3b, v15
	v_exp_f32_e32 v32, v3
	v_mul_f32_e32 v3, 0xbfb8aa3b, v8
	v_exp_f32_e32 v33, v3
	v_lshlrev_b32_e32 v10, 16, v11
	v_and_b32_e32 v11, 0xffff0000, v11
	v_pk_fma_f32 v[6:7], v[26:27], v[6:7], v[10:11]
	v_lshlrev_b32_e32 v10, 16, v4
	v_cvt_pk_bf16_f32 v3, v6, v7
	v_pk_add_f32 v[6:7], v[32:33], 1.0 op_sel_hi:[1,0]
	v_and_b32_e32 v11, 0xffff0000, v4
	v_pk_mul_f32 v[10:11], v[14:15], v[10:11] op_sel_hi:[0,1]
	v_rcp_f32_e32 v4, v7
	s_nop 0
	v_mul_f32_e32 v7, v8, v4
	v_and_b32_e32 v28, 0xffff0000, v9
	v_rcp_f32_e32 v4, v6
	s_nop 0
	v_mul_f32_e32 v6, v15, v4
	v_lshlrev_b32_e32 v15, 16, v9
	v_mul_f32_e32 v4, 0xbfb8aa3b, v15
	v_exp_f32_e32 v26, v4
	v_mul_f32_e32 v4, 0xbfb8aa3b, v28
	v_exp_f32_e32 v27, v4
	v_lshlrev_b32_e32 v8, 16, v12
	v_and_b32_e32 v9, 0xffff0000, v12
	v_pk_fma_f32 v[6:7], v[10:11], v[6:7], v[8:9]
	v_lshlrev_b32_e32 v8, 16, v5
	v_cvt_pk_bf16_f32 v4, v6, v7
	v_pk_add_f32 v[6:7], v[26:27], 1.0 op_sel_hi:[1,0]
	v_and_b32_e32 v9, 0xffff0000, v5
	v_pk_mul_f32 v[8:9], v[14:15], v[8:9] op_sel_hi:[0,1]
	v_rcp_f32_e32 v5, v7
	s_nop 0
	v_mul_f32_e32 v7, v28, v5
	v_rcp_f32_e32 v5, v6
	s_nop 0
	v_mul_f32_e32 v6, v15, v5
	v_lshlrev_b32_e32 v10, 16, v13
	v_and_b32_e32 v11, 0xffff0000, v13
	v_pk_fma_f32 v[6:7], v[8:9], v[6:7], v[10:11]
	s_nop 0
	v_cvt_pk_bf16_f32 v5, v6, v7
	global_store_dwordx4 v[16:17], v[2:5], off
	ds_read_b128 v[14:17], v30 offset:6528
	s_nop 0
	v_add_u32_e32 v2, 24, v29
	v_ashrrev_i32_e32 v2, 3, v2
	v_ashrrev_i32_e32 v3, 31, v2
	v_lshl_add_u64 v[2:3], s[80:81], 0, v[2:3]
	v_mad_u64_u32 v[4:5], s[0:1], v2, s76, v[20:21]
	v_mad_i32_i24 v5, v3, s76, v5
	v_lshl_add_u64 v[4:5], v[4:5], 0, v[0:1]
	v_lshl_add_u64 v[4:5], v[4:5], 0, v[18:19]
	v_add_co_u32_e32 v4, vcc, s35, v4
	s_nop 1
	v_addc_co_u32_e32 v5, vcc, 0, v5, vcc
	global_load_dwordx4 v[10:13], v[4:5], off
	v_mad_u64_u32 v[4:5], s[0:1], v2, s77, v[22:23]
	v_mad_i32_i24 v5, v3, s77, v5
	v_lshl_add_u64 v[4:5], v[4:5], 0, v[24:25]
	global_load_dword v26, v[4:5], off offset:128
	v_lshlrev_b64 v[2:3], 13, v[2:3]
	v_lshl_add_u64 v[2:3], s[44:45], 0, v[2:3]
	v_lshl_add_u64 v[2:3], v[2:3], 0, v[0:1]
	v_lshl_add_u64 v[24:25], v[2:3], 0, v[18:19]
	global_load_dwordx4 v[6:9], v[24:25], off
	s_waitcnt vmcnt(2)
	v_lshlrev_b32_e32 v0, 16, v10
	v_and_b32_e32 v10, 0xffff0000, v10
	v_mul_f32_e32 v2, 0xbfb8aa3b, v0
	v_mul_f32_e32 v3, 0xbfb8aa3b, v10
	v_exp_f32_e32 v2, v2
	v_exp_f32_e32 v3, v3
	s_nop 0
	v_pk_add_f32 v[32:33], v[2:3], 1.0 op_sel_hi:[1,0]
	s_nop 0
	ds_read_b128 v[2:5], v30 offset:7616
	s_waitcnt lgkmcnt(1)
	v_lshlrev_b32_e32 v30, 16, v14
	v_and_b32_e32 v31, 0xffff0000, v14
	s_waitcnt vmcnt(1)
	v_pk_mul_f32 v[30:31], v[26:27], v[30:31] op_sel_hi:[0,1]
	v_rcp_f32_e32 v14, v33
	s_nop 0
	v_mul_f32_e32 v33, v10, v14
	v_rcp_f32_e32 v10, v32
	s_nop 0
	v_mul_f32_e32 v32, v0, v10
	v_lshlrev_b32_e32 v0, 16, v11
	v_and_b32_e32 v27, 0xffff0000, v11
	v_mul_f32_e32 v11, 0xbfb8aa3b, v0
	v_exp_f32_e32 v34, v11
	v_mul_f32_e32 v11, 0xbfb8aa3b, v27
	v_exp_f32_e32 v35, v11
	s_waitcnt vmcnt(0)
	v_lshlrev_b32_e32 v10, 16, v6
	v_and_b32_e32 v11, 0xffff0000, v6
	v_pk_fma_f32 v[10:11], v[30:31], v[32:33], v[10:11]
	v_lshlrev_b32_e32 v14, 16, v15
	v_cvt_pk_bf16_f32 v6, v10, v11
	v_pk_add_f32 v[10:11], v[34:35], 1.0 op_sel_hi:[1,0]
	v_and_b32_e32 v15, 0xffff0000, v15
	v_pk_mul_f32 v[14:15], v[26:27], v[14:15] op_sel_hi:[0,1]
	v_rcp_f32_e32 v28, v11
	s_nop 0
	v_mul_f32_e32 v11, v27, v28
	v_rcp_f32_e32 v27, v10
	s_nop 0
	v_mul_f32_e32 v10, v0, v27
	v_lshlrev_b32_e32 v0, 16, v12
	v_and_b32_e32 v12, 0xffff0000, v12
	v_mul_f32_e32 v27, 0xbfb8aa3b, v0
	v_exp_f32_e32 v32, v27
	v_mul_f32_e32 v27, 0xbfb8aa3b, v12
	v_exp_f32_e32 v33, v27
	v_lshlrev_b32_e32 v30, 16, v7
	v_and_b32_e32 v31, 0xffff0000, v7
	v_pk_fma_f32 v[10:11], v[14:15], v[10:11], v[30:31]
	v_lshlrev_b32_e32 v14, 16, v16
	v_cvt_pk_bf16_f32 v7, v10, v11
	v_pk_add_f32 v[10:11], v[32:33], 1.0 op_sel_hi:[1,0]
	v_and_b32_e32 v15, 0xffff0000, v16
	v_pk_mul_f32 v[14:15], v[26:27], v[14:15] op_sel_hi:[0,1]
	v_rcp_f32_e32 v16, v11
	s_nop 0
	v_mul_f32_e32 v11, v12, v16
	v_rcp_f32_e32 v12, v10
	s_nop 0
	v_mul_f32_e32 v10, v0, v12
	v_lshlrev_b32_e32 v0, 16, v13
	v_and_b32_e32 v16, 0xffff0000, v13
	v_mul_f32_e32 v13, 0xbfb8aa3b, v0
	v_exp_f32_e32 v30, v13
	v_mul_f32_e32 v13, 0xbfb8aa3b, v16
	v_exp_f32_e32 v31, v13
	v_lshlrev_b32_e32 v12, 16, v8
	v_and_b32_e32 v13, 0xffff0000, v8
	v_pk_fma_f32 v[10:11], v[14:15], v[10:11], v[12:13]
	v_lshlrev_b32_e32 v12, 16, v17
	v_cvt_pk_bf16_f32 v8, v10, v11
	v_pk_add_f32 v[10:11], v[30:31], 1.0 op_sel_hi:[1,0]
	v_and_b32_e32 v13, 0xffff0000, v17
	v_pk_mul_f32 v[12:13], v[26:27], v[12:13] op_sel_hi:[0,1]
	v_rcp_f32_e32 v14, v11
	s_nop 0
	v_mul_f32_e32 v11, v16, v14
	v_rcp_f32_e32 v14, v10
	s_nop 0
	v_mul_f32_e32 v10, v0, v14
	v_lshlrev_b32_e32 v14, 16, v9
	v_and_b32_e32 v15, 0xffff0000, v9
	v_pk_fma_f32 v[10:11], v[12:13], v[10:11], v[14:15]
	v_add_u32_e32 v0, 28, v29
	v_cvt_pk_bf16_f32 v9, v10, v11
	global_store_dwordx4 v[24:25], v[6:9], off
	v_and_or_b32 v14, v0, 7, s34
	v_mov_b32_e32 v15, v1
	v_ashrrev_i32_e32 v6, 3, v0
	v_ashrrev_i32_e32 v7, 31, v6
	v_lshl_add_u64 v[10:11], s[80:81], 0, v[6:7]
	v_mad_u64_u32 v[6:7], s[0:1], v10, s76, v[20:21]
	v_mad_i32_i24 v7, v11, s76, v7
	v_lshlrev_b32_e32 v0, 8, v14
	v_lshl_add_u64 v[6:7], v[6:7], 0, v[0:1]
	v_lshl_add_u64 v[6:7], v[6:7], 0, v[18:19]
	v_add_co_u32_e32 v6, vcc, s35, v6
	v_mad_u64_u32 v[12:13], s[0:1], v10, s77, v[22:23]
	s_nop 0
	v_addc_co_u32_e32 v7, vcc, 0, v7, vcc
	global_load_dwordx4 v[6:9], v[6:7], off
	v_mad_i32_i24 v13, v11, s77, v13
	v_lshlrev_b32_e32 v14, 2, v14
	v_lshl_add_u64 v[12:13], v[12:13], 0, v[14:15]
	global_load_dword v14, v[12:13], off offset:128
	v_lshlrev_b64 v[10:11], 13, v[10:11]
	v_lshl_add_u64 v[10:11], s[44:45], 0, v[10:11]
	v_lshl_add_u64 v[10:11], v[10:11], 0, v[0:1]
	v_lshl_add_u64 v[16:17], v[10:11], 0, v[18:19]
	global_load_dwordx4 v[10:13], v[16:17], off
	s_waitcnt lgkmcnt(0)
	v_lshlrev_b32_e32 v20, 16, v2
	v_and_b32_e32 v21, 0xffff0000, v2
	s_waitcnt vmcnt(2)
	v_lshlrev_b32_e32 v0, 16, v6
	v_and_b32_e32 v6, 0xffff0000, v6
	v_mul_f32_e32 v15, 0xbfb8aa3b, v0
	v_exp_f32_e32 v18, v15
	v_mul_f32_e32 v15, 0xbfb8aa3b, v6
	v_exp_f32_e32 v19, v15
	s_nop 0
	v_pk_add_f32 v[18:19], v[18:19], 1.0 op_sel_hi:[1,0]
	s_nop 0
	s_waitcnt vmcnt(1)
	v_pk_mul_f32 v[20:21], v[14:15], v[20:21] op_sel_hi:[0,1]
	v_rcp_f32_e32 v2, v19
	s_nop 0
	v_mul_f32_e32 v19, v6, v2
	v_rcp_f32_e32 v2, v18
	s_nop 0
	v_mul_f32_e32 v18, v0, v2
	v_lshlrev_b32_e32 v0, 16, v7
	v_and_b32_e32 v15, 0xffff0000, v7
	v_mul_f32_e32 v2, 0xbfb8aa3b, v0
	v_exp_f32_e32 v22, v2
	v_mul_f32_e32 v2, 0xbfb8aa3b, v15
	v_exp_f32_e32 v23, v2
	s_waitcnt vmcnt(0)
	v_lshlrev_b32_e32 v6, 16, v10
	v_and_b32_e32 v7, 0xffff0000, v10
	v_pk_fma_f32 v[6:7], v[20:21], v[18:19], v[6:7]
	v_lshlrev_b32_e32 v18, 16, v3
	v_cvt_pk_bf16_f32 v2, v6, v7
	v_pk_add_f32 v[6:7], v[22:23], 1.0 op_sel_hi:[1,0]
	v_and_b32_e32 v19, 0xffff0000, v3
	v_pk_mul_f32 v[18:19], v[14:15], v[18:19] op_sel_hi:[0,1]
	v_rcp_f32_e32 v3, v7
	s_nop 0
	v_mul_f32_e32 v7, v15, v3
	v_rcp_f32_e32 v3, v6
	s_nop 0
	v_mul_f32_e32 v6, v0, v3
	v_lshlrev_b32_e32 v0, 16, v8
	v_and_b32_e32 v8, 0xffff0000, v8
	v_mul_f32_e32 v3, 0xbfb8aa3b, v0
	v_exp_f32_e32 v20, v3
	v_mul_f32_e32 v3, 0xbfb8aa3b, v8
	v_exp_f32_e32 v21, v3
	v_lshlrev_b32_e32 v10, 16, v11
	v_and_b32_e32 v11, 0xffff0000, v11
	v_pk_fma_f32 v[6:7], v[18:19], v[6:7], v[10:11]
	v_lshlrev_b32_e32 v10, 16, v4
	v_cvt_pk_bf16_f32 v3, v6, v7
	v_pk_add_f32 v[6:7], v[20:21], 1.0 op_sel_hi:[1,0]
	v_and_b32_e32 v11, 0xffff0000, v4
	v_pk_mul_f32 v[10:11], v[14:15], v[10:11] op_sel_hi:[0,1]
	v_rcp_f32_e32 v4, v7
	s_nop 0
	v_mul_f32_e32 v7, v8, v4
	v_rcp_f32_e32 v4, v6
	s_nop 0
	v_mul_f32_e32 v6, v0, v4
	v_lshlrev_b32_e32 v0, 16, v9
	v_and_b32_e32 v15, 0xffff0000, v9
	v_mul_f32_e32 v4, 0xbfb8aa3b, v0
	v_exp_f32_e32 v18, v4
	v_mul_f32_e32 v4, 0xbfb8aa3b, v15
	v_exp_f32_e32 v19, v4
	v_lshlrev_b32_e32 v8, 16, v12
	v_and_b32_e32 v9, 0xffff0000, v12
	v_pk_fma_f32 v[6:7], v[10:11], v[6:7], v[8:9]
	v_lshlrev_b32_e32 v8, 16, v5
	v_cvt_pk_bf16_f32 v4, v6, v7
	v_pk_add_f32 v[6:7], v[18:19], 1.0 op_sel_hi:[1,0]
	v_and_b32_e32 v9, 0xffff0000, v5
	v_pk_mul_f32 v[8:9], v[14:15], v[8:9] op_sel_hi:[0,1]
	v_rcp_f32_e32 v5, v7
	s_nop 0
	v_mul_f32_e32 v7, v15, v5
	s_max_i32 s0, s67, 0x1ff
	s_addk_i32 s0, 0xfe01
	v_rcp_f32_e32 v5, v6
	s_nop 0
	v_mul_f32_e32 v6, v0, v5
	v_lshlrev_b32_e32 v10, 16, v13
	v_and_b32_e32 v11, 0xffff0000, v13
	s_lshr_b32 s12, s0, 6
	s_ashr_i32 s0, s31, 1
	v_pk_fma_f32 v[6:7], v[8:9], v[6:7], v[10:11]
	s_sub_i32 s14, s0, s12
	v_cvt_pk_bf16_f32 v5, v6, v7
	v_cmp_ge_i32_e32 vcc, s14, v176
	global_store_dwordx4 v[16:17], v[2:5], off
	s_barrier
	s_and_saveexec_b64 s[0:1], vcc
	v_add_u32_e32 v0, s12, v176
	ds_write_b32 v179, v0
	s_or_b64 exec, exec, s[0:1]
	v_mov_b32_e32 v79, 0
	s_cmp_lt_i32 s14, 0
	v_mov_b32_e32 v78, 0
	v_mov_b32_e32 v77, 0
	v_mov_b32_e32 v76, 0
	v_mov_b32_e32 v75, 0
	v_mov_b32_e32 v74, 0
	v_mov_b32_e32 v73, 0
	v_mov_b32_e32 v72, 0
	v_mov_b32_e32 v71, 0
	v_mov_b32_e32 v70, 0
	v_mov_b32_e32 v69, 0
	v_mov_b32_e32 v68, 0
	v_mov_b32_e32 v67, 0
	v_mov_b32_e32 v66, 0
	v_mov_b32_e32 v65, 0
	v_mov_b32_e32 v64, 0
	v_mov_b32_e32 v63, 0
	v_mov_b32_e32 v62, 0
	v_mov_b32_e32 v61, 0
	v_mov_b32_e32 v60, 0
	v_mov_b32_e32 v59, 0
	v_mov_b32_e32 v58, 0
	v_mov_b32_e32 v57, 0
	v_mov_b32_e32 v56, 0
	v_mov_b32_e32 v55, 0
	v_mov_b32_e32 v54, 0
	v_mov_b32_e32 v53, 0
	v_mov_b32_e32 v52, 0
	v_mov_b32_e32 v51, 0
	v_mov_b32_e32 v50, 0
	v_mov_b32_e32 v49, 0
	v_mov_b32_e32 v48, 0
	v_mov_b32_e32 v47, 0
	v_mov_b32_e32 v46, 0
	v_mov_b32_e32 v45, 0
	v_mov_b32_e32 v44, 0
	v_mov_b32_e32 v43, 0
	v_mov_b32_e32 v42, 0
	v_mov_b32_e32 v41, 0
	v_mov_b32_e32 v40, 0
	v_mov_b32_e32 v39, 0
	v_mov_b32_e32 v38, 0
	v_mov_b32_e32 v37, 0
	v_mov_b32_e32 v36, 0
	v_mov_b32_e32 v35, 0
	v_mov_b32_e32 v34, 0
	v_mov_b32_e32 v33, 0
	v_mov_b32_e32 v32, 0
	v_mov_b32_e32 v31, 0
	v_mov_b32_e32 v30, 0
	v_mov_b32_e32 v29, 0
	v_mov_b32_e32 v28, 0
	v_mov_b32_e32 v27, 0
	v_mov_b32_e32 v26, 0
	v_mov_b32_e32 v25, 0
	v_mov_b32_e32 v24, 0
	v_mov_b32_e32 v23, 0
	v_mov_b32_e32 v22, 0
	v_mov_b32_e32 v21, 0
	v_mov_b32_e32 v20, 0
	v_mov_b32_e32 v19, 0
	v_mov_b32_e32 v18, 0
	v_mov_b32_e32 v17, 0
	v_mov_b32_e32 v16, 0
	v_mov_b32_e32 v170, 0
	s_waitcnt lgkmcnt(0)
	s_barrier
	s_cbranch_scc1 .LBB0_1058
	v_mov_b32_e32 v0, s92
	ds_read_b32 v2, v0
	s_lshl_b64 s[0:1], s[20:21], 1
	v_readlane_b32 s12, v255, 24
	s_add_u32 s12, s12, s0
	v_readlane_b32 s13, v255, 25
	s_addc_u32 s13, s13, s1
	v_readlane_b32 s15, v255, 26
	s_add_u32 s0, s15, s0
	v_readlane_b32 s15, v255, 27
	s_waitcnt lgkmcnt(0)
	v_ashrrev_i32_e32 v3, 31, v2
	v_readfirstlane_b32 s99, v2
	s_addc_u32 s1, s15, s1
	v_lshlrev_b64 v[4:5], 14, v[2:3]
	v_lshl_add_u64 v[4:5], s[0:1], 0, v[4:5]
	v_lshl_add_u64 v[4:5], v[4:5], 0, v[146:147]
	v_lshlrev_b64 v[2:3], 7, v[2:3]
	v_add_co_u32_e32 v6, vcc, s35, v4
	v_lshl_add_u64 v[2:3], s[12:13], 0, v[2:3]
	s_nop 0
	v_addc_co_u32_e32 v7, vcc, 0, v5, vcc
	v_lshl_add_u64 v[2:3], v[2:3], 0, v[162:163]
	s_mov_b32 s15, 0x80000
	global_load_dwordx4 v[64:67], v[4:5], off
	global_load_dwordx4 v[68:71], v[6:7], off
	v_add_co_u32_e32 v4, vcc, s15, v2
	v_mov_b32_e32 v14, v1
	s_nop 0
	v_addc_co_u32_e32 v5, vcc, 0, v3, vcc
	global_load_dwordx4 v[72:75], v[2:3], off
	global_load_dwordx4 v[76:79], v[4:5], off
	v_mov_b32_e32 v15, v1
	v_mov_b32_e32 v0, v1
	v_mov_b32_e32 v2, v1
	v_mov_b32_e32 v3, v1
	v_mov_b32_e32 v4, v1
	v_mov_b32_e32 v5, v1
	v_mov_b32_e32 v6, v1
	v_mov_b32_e32 v7, v1
	v_mov_b32_e32 v8, v1
	v_mov_b32_e32 v9, v1
	v_mov_b32_e32 v10, v1
	v_mov_b32_e32 v11, v1
	v_mov_b32_e32 v12, v1
	v_mov_b32_e32 v13, v1
	v_mov_b64_e32 v[30:31], v[14:15]
	v_mov_b64_e32 v[46:47], v[14:15]
	v_mov_b64_e32 v[62:63], v[14:15]
	s_mov_b32 s15, 0
	v_sub_u32_e32 v171, v221, v168
	v_mov_b32_e32 v170, 0
	v_mov_b32_e32 v142, 0xf149f2ca
	v_mov_b32_e32 v130, 0
	v_mov_b32_e32 v131, 0
	v_mov_b32_e32 v132, 0
	v_mov_b32_e32 v133, 0
	v_mov_b32_e32 v134, 0
	v_mov_b32_e32 v135, 0
	v_mov_b32_e32 v136, 0
	v_mov_b32_e32 v137, 0
	v_mov_b64_e32 v[28:29], v[12:13]
	v_mov_b64_e32 v[26:27], v[10:11]
	v_mov_b64_e32 v[24:25], v[8:9]
	v_mov_b64_e32 v[22:23], v[6:7]
	v_mov_b64_e32 v[20:21], v[4:5]
	v_mov_b64_e32 v[18:19], v[2:3]
	v_mov_b64_e32 v[16:17], v[0:1]
	v_mov_b64_e32 v[44:45], v[12:13]
	v_mov_b64_e32 v[42:43], v[10:11]
	v_mov_b64_e32 v[40:41], v[8:9]
	v_mov_b64_e32 v[38:39], v[6:7]
	v_mov_b64_e32 v[36:37], v[4:5]
	v_mov_b64_e32 v[34:35], v[2:3]
	v_mov_b64_e32 v[32:33], v[0:1]
	v_mov_b64_e32 v[60:61], v[12:13]
	v_mov_b64_e32 v[58:59], v[10:11]
	v_mov_b64_e32 v[56:57], v[8:9]
	v_mov_b64_e32 v[54:55], v[6:7]
	v_mov_b64_e32 v[52:53], v[4:5]
	v_mov_b64_e32 v[50:51], v[2:3]
	v_mov_b64_e32 v[48:49], v[0:1]
	v_lshl_add_u64 v[96:97], s[12:13], 0, v[162:163]
	s_add_i32 s16, 0, 0x1bb04
	s_add_i32 s17, s14, 1
	v_lshl_add_u64 v[168:169], s[0:1], 0, v[146:147]
	s_waitcnt vmcnt(3)
	ds_write_b128 v225, v[64:67]
	s_waitcnt vmcnt(2)
	ds_write_b128 v225, v[68:71] offset:8704
	s_waitcnt vmcnt(1)
	ds_write2_b64 v167, v[72:73], v[74:75] offset0:128 offset1:130
	s_waitcnt vmcnt(0)
	ds_write2_b64 v232, v[76:77], v[78:79] offset1:2
	v_mov_b64_e32 v[78:79], v[14:15]
	v_mov_b64_e32 v[76:77], v[12:13]
	v_mov_b64_e32 v[74:75], v[10:11]
	v_mov_b64_e32 v[72:73], v[8:9]
	v_mov_b64_e32 v[70:71], v[6:7]
	v_mov_b64_e32 v[68:69], v[4:5]
	v_mov_b64_e32 v[66:67], v[2:3]
	v_mov_b64_e32 v[64:65], v[0:1]
	s_waitcnt lgkmcnt(0)
	s_barrier
	s_branch .LBB0_1234

.LBB0_1234:
	s_add_i32 s0, s99, s15
	v_mov_b32_e32 v0, s0
	s_cmp_lt_i32 s15, s14
	s_cselect_b64 s[0:1], -1, 0
	s_cmp_ge_i32 s15, s14
	v_mov_b32_e32 v14, v0
	s_cbranch_scc1 .LBB0_1236
	v_add_u32_e32 v14, 1, v0
.LBB0_1236:
	v_cndmask_b32_e64 v10, 0, 1, s[0:1]
	v_cmp_ne_u32_e64 s[12:13], 1, v10
	s_andn2_b64 vcc, exec, s[0:1]
	v_ashrrev_i32_e32 v15, 31, v14
	s_cbranch_vccnz .LBB0_1238
	s_waitcnt vmcnt(1)
	v_lshlrev_b64 v[2:3], 14, v[14:15]
	v_lshl_add_u64 v[2:3], v[168:169], 0, v[2:3]
	s_waitcnt vmcnt(0)
	v_add_co_u32_e32 v6, vcc, 0x2000, v2
	s_nop 1
	v_addc_co_u32_e32 v7, vcc, 0, v3, vcc
	global_load_dwordx4 v[2:5], v[2:3], off
	s_nop 0
	global_load_dwordx4 v[6:9], v[6:7], off

	.amdhsa_kernel _Z10fwd_kernel6Params
		.amdhsa_group_segment_fixed_size 0
		.amdhsa_private_segment_fixed_size 0
		.amdhsa_kernarg_size 440
		.amdhsa_user_sgpr_count 2
		.amdhsa_user_sgpr_dispatch_ptr 0
		.amdhsa_user_sgpr_queue_ptr 0
		.amdhsa_user_sgpr_kernarg_segment_ptr 1
		.amdhsa_user_sgpr_dispatch_id 0
		.amdhsa_user_sgpr_kernarg_preload_length 0
		.amdhsa_user_sgpr_kernarg_preload_offset 0
		.amdhsa_user_sgpr_private_segment_size 0
		.amdhsa_uses_dynamic_stack 0
		.amdhsa_enable_private_segment 0
		.amdhsa_system_sgpr_workgroup_id_x 1
		.amdhsa_system_sgpr_workgroup_id_y 0
		.amdhsa_system_sgpr_workgroup_id_z 0
		.amdhsa_system_sgpr_workgroup_info 0
		.amdhsa_system_vgpr_workitem_id 2
		.amdhsa_next_free_vgpr 256
		.amdhsa_next_free_sgpr 100
		.amdhsa_accum_offset 256
		.amdhsa_reserve_vcc 1
		.amdhsa_float_round_mode_32 0
		.amdhsa_float_round_mode_16_64 0
		.amdhsa_float_denorm_mode_32 3
		.amdhsa_float_denorm_mode_16_64 3
		.amdhsa_dx10_clamp 1
		.amdhsa_ieee_mode 1
		.amdhsa_fp16_overflow 0
		.amdhsa_tg_split 0
		.amdhsa_exception_fp_ieee_invalid_op 0
		.amdhsa_exception_fp_denorm_src 0
		.amdhsa_exception_fp_ieee_div_zero 0
		.amdhsa_exception_fp_ieee_overflow 0
		.amdhsa_exception_fp_ieee_underflow 0
		.amdhsa_exception_fp_ieee_inexact 0
		.amdhsa_exception_int_div_zero 0
	.end_amdhsa_kernel

amdhsa.kernels:
  - .agpr_count:     0
    .args:
      - .offset:         0
        .size:           184
        .value_kind:     by_value
      - .offset:         184
        .size:           4
        .value_kind:     hidden_block_count_x
      - .offset:         188
        .size:           4
        .value_kind:     hidden_block_count_y
      - .offset:         192
        .size:           4
        .value_kind:     hidden_block_count_z
      - .offset:         196
        .size:           2
        .value_kind:     hidden_group_size_x
      - .offset:         198
        .size:           2
        .value_kind:     hidden_group_size_y
      - .offset:         200
        .size:           2
        .value_kind:     hidden_group_size_z
      - .offset:         202
        .size:           2
        .value_kind:     hidden_remainder_x
      - .offset:         204
        .size:           2
        .value_kind:     hidden_remainder_y
      - .offset:         206
        .size:           2
        .value_kind:     hidden_remainder_z
      - .offset:         224
        .size:           8
        .value_kind:     hidden_global_offset_x
      - .offset:         232
        .size:           8
        .value_kind:     hidden_global_offset_y
      - .offset:         240
        .size:           8
        .value_kind:     hidden_global_offset_z
      - .offset:         248
        .size:           2
        .value_kind:     hidden_grid_dims
      - .offset:         272
        .size:           8
        .value_kind:     hidden_multigrid_sync_arg
      - .offset:         304
        .size:           4
        .value_kind:     hidden_dynamic_lds_size
    .group_segment_fixed_size: 0
    .kernarg_segment_align: 8
    .kernarg_segment_size: 440
    .language:       OpenCL C
    .language_version:
      - 2
      - 0
    .max_flat_workgroup_size: 512
    .name:           _Z10fwd_kernel6Params
    .private_segment_fixed_size: 0
    .sgpr_count:     106
    .sgpr_spill_count: 34
    .symbol:         _Z10fwd_kernel6Params.kd
    .uniform_work_group_size: 1
    .uses_dynamic_stack: false
    .vgpr_count:     256
    .vgpr_spill_count: 0
    .wavefront_size: 64
